# cross-half softmax max exchange via v_permlane32_swap instead of ds_bpermute + LDS wait (MLA and natten loops)
# speedup vs baseline: 1.0088x; 1.0065x over previous
.LBB0_347:
	s_bitcmp1_b32 s85, 0
	s_cselect_b32 s3, 0x2c00, 0
	s_cmp_gt_i32 s85, s97
	s_mov_b64 s[86:87], -1
	s_cbranch_scc1 .LBB0_435
	v_add_u32_e32 v2, s85, v195
	v_cmp_ge_u32_e32 vcc, v2, v194
	v_cmp_lt_u32_e64 s[86:87], v2, v214
	v_mov_b32_e32 v221, v163
	v_mov_b32_e32 v166, v0
	v_mov_b32_e32 v222, v220
	v_mov_b32_e32 v162, v219
	s_and_b64 vcc, vcc, s[86:87]
	s_and_saveexec_b64 s[86:87], vcc
	s_cbranch_execz .LBB0_434
	v_lshl_add_u32 v162, s3, 1, v215
	v_mov_b32_e32 v189, 0xff800000
	ds_read2_b32 v[168:169], v218 offset0:8 offset1:9
	ds_read2_b32 v[170:171], v218 offset0:10 offset1:11
	ds_read2_b32 v[172:173], v218 offset0:16 offset1:17
	ds_read2_b32 v[174:175], v218 offset0:18 offset1:19
	ds_read2_b32 v[176:177], v218 offset0:24 offset1:25
	ds_read2_b32 v[178:179], v218 offset0:26 offset1:27
	ds_read2_b32 v[180:181], v218 offset0:32 offset1:33
	ds_read2_b32 v[182:183], v218 offset0:34 offset1:35
	ds_read2_b32 v[22:23], v218 offset0:40 offset1:41
	ds_read2_b32 v[24:25], v218 offset0:42 offset1:43
	ds_read2_b32 v[18:19], v218 offset0:0 offset1:1
	ds_read2_b32 v[20:21], v218 offset0:2 offset1:3
	ds_read_b128 v[2:5], v162
	ds_read_b128 v[184:187], v162 offset:32
	ds_read_b128 v[54:57], v192 offset:47104
	ds_read_b128 v[58:61], v192 offset:47136
	s_waitcnt lgkmcnt(3)
	v_mfma_f32_32x32x16_bf16 v[38:53], v[2:5], v[130:133], v[168:183]
	s_waitcnt lgkmcnt(1)
	v_mfma_f32_32x32x16_bf16 v[6:21], v[2:5], v[54:57], v[6:21]
	ds_read_b128 v[2:5], v162 offset:64
	ds_read_b128 v[62:65], v192 offset:47168
	v_mfma_f32_32x32x16_bf16 v[38:53], v[184:187], v[134:137], v[38:53]
	s_waitcnt lgkmcnt(2)
	v_mfma_f32_32x32x16_bf16 v[6:21], v[184:187], v[58:61], v[6:21]
	s_waitcnt lgkmcnt(1)
	v_mfma_f32_32x32x16_bf16 v[38:53], v[2:5], v[138:141], v[38:53]
	s_waitcnt lgkmcnt(0)
	v_mfma_f32_32x32x16_bf16 v[6:21], v[2:5], v[62:65], v[6:21]
	ds_read_b128 v[2:5], v162 offset:96
	ds_read_b128 v[164:167], v192 offset:47200
	s_waitcnt lgkmcnt(1)
	v_mfma_f32_32x32x16_bf16 v[38:53], v[2:5], v[142:145], v[38:53]
	s_waitcnt lgkmcnt(0)
	v_mfma_f32_32x32x16_bf16 v[6:21], v[2:5], v[164:167], v[6:21]
	ds_read_b128 v[2:5], v162 offset:4608
	s_waitcnt lgkmcnt(0)
	v_mfma_f32_32x32x16_bf16 v[22:37], v[2:5], v[130:133], v[22:37]
	v_mfma_f32_32x32x16_bf16 v[2:17], v[2:5], v[54:57], v[168:183]
	ds_read_b128 v[54:57], v162 offset:4640
	s_waitcnt lgkmcnt(0)
	v_mfma_f32_32x32x16_bf16 v[22:37], v[54:57], v[134:137], v[22:37]
	v_mfma_f32_32x32x16_bf16 v[2:17], v[54:57], v[58:61], v[2:17]
	ds_read_b128 v[54:57], v162 offset:4672
	s_waitcnt lgkmcnt(0)
	v_mfma_f32_32x32x16_bf16 v[22:37], v[54:57], v[138:141], v[22:37]
	v_mfma_f32_32x32x16_bf16 v[2:17], v[54:57], v[62:65], v[2:17]
	ds_read_b128 v[54:57], v162 offset:4704
	s_waitcnt lgkmcnt(0)
	v_mfma_f32_32x32x16_bf16 v[22:37], v[54:57], v[142:145], v[22:37]
	v_mfma_f32_32x32x16_bf16 v[2:17], v[54:57], v[164:167], v[2:17]
	v_cndmask_b32_e64 v164, v189, v46, s[18:19]
	v_cndmask_b32_e64 v162, v189, v47, s[20:21]
	v_cndmask_b32_e64 v177, v189, v48, s[22:23]
	v_cndmask_b32_e64 v178, v189, v49, s[24:25]
	v_cndmask_b32_e64 v179, v189, v50, s[26:27]
	v_cndmask_b32_e64 v166, v189, v51, s[28:29]
	v_cndmask_b32_e64 v181, v189, v52, s[30:31]
	v_cndmask_b32_e64 v182, v189, v53, s[34:35]
	s_nop 2
	v_cndmask_b32_e64 v27, v189, v38, s[0:1]
	v_cndmask_b32_e64 v26, v189, v39, s[4:5]
	v_cndmask_b32_e64 v29, v189, v40, s[6:7]
	v_cndmask_b32_e64 v28, v189, v41, s[8:9]
	v_cndmask_b32_e64 v31, v189, v42, s[10:11]
	v_cndmask_b32_e64 v30, v189, v43, s[12:13]
	v_cndmask_b32_e64 v33, v189, v44, s[14:15]
	v_cndmask_b32_e64 v32, v189, v45, s[16:17]
	v_cndmask_b32_e64 v183, v189, v22, s[36:37]
	v_cndmask_b32_e64 v184, v189, v23, s[38:39]
	v_cndmask_b32_e64 v185, v189, v24, s[40:41]
	v_cndmask_b32_e64 v23, v189, v25, s[42:43]
	v_and_b32_e32 v24, 64, v200
	v_xor_b32_e32 v22, 32, v200
	v_add_u32_e32 v24, 64, v24
	v_cmp_lt_i32_e32 vcc, v22, v24
	s_nop 1
	v_cndmask_b32_e32 v22, v200, v22, vcc
	v_lshlrev_b32_e32 v22, 2, v22
	v_max3_f32 v24, v27, v26, v29
	v_max3_f32 v24, v24, v28, v31
	v_max3_f32 v24, v24, v30, v33
	v_max3_f32 v24, v24, v32, v164
	v_max3_f32 v24, v24, v162, v177
	v_max3_f32 v24, v24, v178, v179
	v_max3_f32 v24, v24, v166, v181
	v_max3_f32 v24, v24, v182, v183
	v_max3_f32 v24, v24, v184, v185
	s_mov_b32 s88, 0xff800000
	v_max3_f32 v24, v24, v23, s88
	v_mov_b32_e32 v25, v24
	s_nop 1
	v_permlane32_swap_b32_e32 v24, v25
	v_max_f32_e32 v25, v25, v25
	v_max_f32_e32 v24, v24, v25
	v_add_f32_e32 v25, 0xc1000000, v24
	v_cmp_gt_f32_e32 vcc, v25, v163
	v_mov_b32_e32 v165, v220
	v_mov_b32_e32 v221, v163
	s_cbranch_vccz .LBB0_391
	v_max_f32_e32 v24, v24, v24
	v_max_f32_e32 v25, v163, v163
	v_max_f32_e32 v221, v25, v24
	v_sub_f32_e32 v24, v163, v221
	v_exp_f32_e32 v24, v24
	s_nop 0
	v_mul_f32_e32 v165, v220, v24
	v_pk_mul_f32 v[128:129], v[128:129], v[24:25] op_sel_hi:[1,0]
	v_pk_mul_f32 v[126:127], v[126:127], v[24:25] op_sel_hi:[1,0]
	v_pk_mul_f32 v[124:125], v[124:125], v[24:25] op_sel_hi:[1,0]
	v_pk_mul_f32 v[122:123], v[122:123], v[24:25] op_sel_hi:[1,0]
	v_pk_mul_f32 v[120:121], v[120:121], v[24:25] op_sel_hi:[1,0]
	v_pk_mul_f32 v[118:119], v[118:119], v[24:25] op_sel_hi:[1,0]
	v_pk_mul_f32 v[116:117], v[116:117], v[24:25] op_sel_hi:[1,0]
	v_pk_mul_f32 v[114:115], v[114:115], v[24:25] op_sel_hi:[1,0]
	v_pk_mul_f32 v[112:113], v[112:113], v[24:25] op_sel_hi:[1,0]
	v_pk_mul_f32 v[110:111], v[110:111], v[24:25] op_sel_hi:[1,0]
	v_pk_mul_f32 v[108:109], v[108:109], v[24:25] op_sel_hi:[1,0]
	v_pk_mul_f32 v[106:107], v[106:107], v[24:25] op_sel_hi:[1,0]
	v_pk_mul_f32 v[104:105], v[104:105], v[24:25] op_sel_hi:[1,0]
	v_pk_mul_f32 v[102:103], v[102:103], v[24:25] op_sel_hi:[1,0]
	v_pk_mul_f32 v[100:101], v[100:101], v[24:25] op_sel_hi:[1,0]
	v_pk_mul_f32 v[98:99], v[98:99], v[24:25] op_sel_hi:[1,0]
.LBB0_391:
	v_sub_f32_e32 v24, v27, v221
	v_exp_f32_e32 v167, v24
	v_sub_f32_e32 v24, v26, v221
	v_exp_f32_e32 v168, v24
	v_sub_f32_e32 v24, v29, v221
	v_exp_f32_e32 v169, v24
	v_sub_f32_e32 v24, v28, v221
	v_exp_f32_e32 v170, v24
	v_sub_f32_e32 v24, v31, v221
	v_exp_f32_e32 v171, v24
	v_sub_f32_e32 v24, v30, v221
	v_exp_f32_e32 v172, v24
	v_sub_f32_e32 v24, v33, v221
	v_exp_f32_e32 v173, v24
	v_sub_f32_e32 v24, v32, v221
	v_exp_f32_e32 v174, v24
	v_sub_f32_e32 v24, v164, v221
	v_exp_f32_e32 v175, v24
	v_sub_f32_e32 v24, v162, v221
	v_lshl_add_u32 v180, s3, 1, v216
	v_exp_f32_e32 v176, v24
	v_sub_f32_e32 v24, v177, v221
	v_exp_f32_e32 v177, v24
	v_sub_f32_e32 v24, v178, v221
	v_add_u32_e32 v162, 0x3000, v180
	v_exp_f32_e32 v178, v24
	ds_read2_b64 v[24:27], v162 offset0:128 offset1:130
	v_sub_f32_e32 v28, v179, v221
	v_exp_f32_e32 v179, v28
	v_cvt_pk_bf16_f32 v28, v167, v168
	v_cvt_pk_bf16_f32 v29, v169, v170
	v_cvt_pk_bf16_f32 v30, v171, v172
	v_cvt_pk_bf16_f32 v31, v173, v174
	v_add_u32_e32 v164, 0x4000, v180
	ds_read2_b64 v[186:189], v164 offset0:192 offset1:194
	s_waitcnt lgkmcnt(1)
	v_mfma_f32_32x32x16_bf16 v[114:129], v[24:27], v[28:31], v[114:129]
	v_sub_f32_e32 v24, v166, v221
	v_exp_f32_e32 v180, v24
	v_sub_f32_e32 v24, v181, v221
	v_exp_f32_e32 v181, v24
	v_sub_f32_e32 v24, v182, v221
	v_exp_f32_e32 v182, v24
	ds_read2_b64 v[24:27], v162 offset0:132 offset1:134
	s_waitcnt lgkmcnt(1)
	v_mfma_f32_32x32x16_bf16 v[98:113], v[186:189], v[28:31], v[98:113]
	v_sub_f32_e32 v28, v183, v221
	v_exp_f32_e32 v183, v28
	v_cvt_pk_bf16_f32 v28, v175, v176
	v_cvt_pk_bf16_f32 v29, v177, v178
	v_cvt_pk_bf16_f32 v30, v179, v180
	v_cvt_pk_bf16_f32 v31, v181, v182
	ds_read2_b64 v[222:225], v164 offset0:196 offset1:198
	v_sub_f32_e32 v23, v23, v221
	s_waitcnt lgkmcnt(1)
	v_mfma_f32_32x32x16_bf16 v[114:129], v[24:27], v[28:31], v[114:129]
	v_sub_f32_e32 v24, v184, v221
	v_exp_f32_e32 v184, v24
	v_sub_f32_e32 v24, v185, v221
	v_exp_f32_e32 v185, v24
	ds_read2_b64 v[24:27], v162 offset0:136 offset1:138
	v_exp_f32_e32 v186, v23
	v_sub_f32_e32 v23, 0xff800000, v221
	v_exp_f32_e32 v187, v23
	s_waitcnt lgkmcnt(1)
	v_mfma_f32_32x32x16_bf16 v[98:113], v[222:225], v[28:31], v[98:113]
	v_cvt_pk_bf16_f32 v28, v183, v184
	v_cvt_pk_bf16_f32 v29, v185, v186
	v_cvt_pk_bf16_f32 v30, v187, v187
	v_mov_b32_e32 v31, v30
	v_mov_b32_e32 v188, 0xff800000
	s_waitcnt lgkmcnt(0)
	v_mfma_f32_32x32x16_bf16 v[114:129], v[24:27], v[28:31], v[114:129]
	ds_read2_b64 v[24:27], v164 offset0:200 offset1:202
	s_waitcnt lgkmcnt(0)
	v_mfma_f32_32x32x16_bf16 v[98:113], v[24:27], v[28:31], v[98:113]
	v_mov_b32_e32 v23, 0xff800000
	v_cndmask_b32_e64 v189, v23, v18, s[44:45]
	v_cndmask_b32_e64 v188, v23, v19, s[46:47]
	v_cndmask_b32_e64 v209, v23, v20, s[48:49]
	v_cndmask_b32_e64 v208, v23, v21, s[50:51]
	v_cndmask_b32_e64 v225, v23, v2, s[52:53]
	v_cndmask_b32_e64 v223, v23, v3, s[54:55]
	v_cndmask_b32_e64 v233, v23, v4, s[56:57]
	v_cndmask_b32_e64 v231, v23, v5, s[58:59]
	v_cndmask_b32_e64 v237, v23, v6, s[60:61]
	v_cndmask_b32_e64 v212, v23, v7, s[62:63]
	v_cndmask_b32_e64 v227, v23, v8, s[64:65]
	v_cndmask_b32_e64 v224, v23, v9, s[66:67]
	v_cndmask_b32_e64 v235, v23, v10, s[68:69]
	v_cndmask_b32_e64 v229, v23, v11, s[70:71]
	v_cndmask_b32_e64 v234, v23, v12, s[72:73]
	v_cndmask_b32_e64 v226, v23, v13, s[74:75]
	v_cndmask_b32_e64 v230, v23, v14, s[76:77]
	v_cndmask_b32_e64 v228, v23, v15, s[78:79]
	v_cndmask_b32_e64 v236, v23, v16, s[80:81]
	v_cndmask_b32_e64 v232, v23, v17, s[82:83]
	v_max3_f32 v2, v189, s88, v188
	v_max3_f32 v2, v2, v209, v208
	v_max3_f32 v2, v2, v225, v223
	v_max3_f32 v2, v2, v233, v231
	v_max3_f32 v2, v2, v237, v212
	v_max3_f32 v2, v2, v227, v224
	v_max3_f32 v2, v2, v235, v229
	v_max3_f32 v2, v2, v234, v226
	v_max3_f32 v2, v2, v230, v228
	v_max3_f32 v2, v2, v236, v232
	v_mov_b32_e32 v3, v2
	s_nop 1
	v_permlane32_swap_b32_e32 v2, v3
	v_max_f32_e32 v3, v3, v3
	v_max_f32_e32 v222, v2, v3
	v_add_f32_e32 v238, 0xc1000000, v222
	v_cmp_gt_f32_e32 vcc, v238, v0
	v_mov_b32_e32 v238, v219
	v_mov_b32_e32 v166, v0
	s_cbranch_vccz .LBB0_433
	v_max_f32_e32 v2, v222, v222
	v_max_f32_e32 v3, v0, v0
	v_max_f32_e32 v166, v3, v2
	v_sub_f32_e32 v2, v0, v166
	v_exp_f32_e32 v2, v2
	s_nop 0
	v_mul_f32_e32 v238, v219, v2
	v_pk_mul_f32 v[96:97], v[96:97], v[2:3] op_sel_hi:[1,0]
	v_pk_mul_f32 v[94:95], v[94:95], v[2:3] op_sel_hi:[1,0]
	v_pk_mul_f32 v[92:93], v[92:93], v[2:3] op_sel_hi:[1,0]
	v_pk_mul_f32 v[90:91], v[90:91], v[2:3] op_sel_hi:[1,0]
	v_pk_mul_f32 v[88:89], v[88:89], v[2:3] op_sel_hi:[1,0]
	v_pk_mul_f32 v[86:87], v[86:87], v[2:3] op_sel_hi:[1,0]
	v_pk_mul_f32 v[84:85], v[84:85], v[2:3] op_sel_hi:[1,0]
	v_pk_mul_f32 v[82:83], v[82:83], v[2:3] op_sel_hi:[1,0]
	v_pk_mul_f32 v[80:81], v[80:81], v[2:3] op_sel_hi:[1,0]
	v_pk_mul_f32 v[78:79], v[78:79], v[2:3] op_sel_hi:[1,0]
	v_pk_mul_f32 v[76:77], v[76:77], v[2:3] op_sel_hi:[1,0]
	v_pk_mul_f32 v[74:75], v[74:75], v[2:3] op_sel_hi:[1,0]
	v_pk_mul_f32 v[72:73], v[72:73], v[2:3] op_sel_hi:[1,0]
	v_pk_mul_f32 v[70:71], v[70:71], v[2:3] op_sel_hi:[1,0]
	v_pk_mul_f32 v[68:69], v[68:69], v[2:3] op_sel_hi:[1,0]
	v_pk_mul_f32 v[66:67], v[66:67], v[2:3] op_sel_hi:[1,0]

.LBB0_435:
	s_andn2_b64 vcc, exec, s[86:87]
	s_cbranch_vccnz .LBB0_442
	v_lshl_add_u32 v162, s3, 1, v215
	s_nop 6
	ds_read_b128 v[2:5], v162
	ds_read_b128 v[6:9], v162 offset:32
	ds_read_b128 v[10:13], v192 offset:47104
	ds_read_b128 v[164:167], v192 offset:47136
	s_waitcnt lgkmcnt(3)
	v_mfma_f32_32x32x16_bf16 v[34:49], v[2:5], v[130:133], 0
	s_waitcnt lgkmcnt(1)
	v_mfma_f32_32x32x16_bf16 v[18:33], v[2:5], v[10:13], 0
	ds_read_b128 v[2:5], v162 offset:64
	ds_read_b128 v[168:171], v192 offset:47168
	v_mfma_f32_32x32x16_bf16 v[34:49], v[6:9], v[134:137], v[34:49]
	s_waitcnt lgkmcnt(2)
	v_mfma_f32_32x32x16_bf16 v[18:33], v[6:9], v[164:167], v[18:33]
	s_waitcnt lgkmcnt(1)
	v_mfma_f32_32x32x16_bf16 v[34:49], v[2:5], v[138:141], v[34:49]
	s_waitcnt lgkmcnt(0)
	v_mfma_f32_32x32x16_bf16 v[18:33], v[2:5], v[168:171], v[18:33]
	ds_read_b128 v[2:5], v162 offset:96
	ds_read_b128 v[172:175], v192 offset:47200
	ds_read_b128 v[176:179], v162 offset:4640
	s_waitcnt lgkmcnt(2)
	v_mfma_f32_32x32x16_bf16 v[34:49], v[2:5], v[142:145], v[34:49]
	s_waitcnt lgkmcnt(1)
	v_mfma_f32_32x32x16_bf16 v[18:33], v[2:5], v[172:175], v[18:33]
	ds_read_b128 v[2:5], v162 offset:4608
	s_waitcnt lgkmcnt(0)
	v_mfma_f32_32x32x16_bf16 v[50:65], v[2:5], v[130:133], 0
	v_mfma_f32_32x32x16_bf16 v[2:17], v[2:5], v[10:13], 0
	v_mfma_f32_32x32x16_bf16 v[2:17], v[176:179], v[164:167], v[2:17]
	ds_read_b128 v[164:167], v162 offset:4672
	v_mfma_f32_32x32x16_bf16 v[50:65], v[176:179], v[134:137], v[50:65]
	s_waitcnt lgkmcnt(0)
	v_mfma_f32_32x32x16_bf16 v[50:65], v[164:167], v[138:141], v[50:65]
	v_mfma_f32_32x32x16_bf16 v[2:17], v[164:167], v[168:171], v[2:17]
	ds_read_b128 v[164:167], v162 offset:4704
	v_xor_b32_e32 v162, 32, v200
	s_waitcnt lgkmcnt(0)
	v_mfma_f32_32x32x16_bf16 v[50:65], v[164:167], v[142:145], v[50:65]
	v_mfma_f32_32x32x16_bf16 v[2:17], v[164:167], v[172:175], v[2:17]
	v_and_b32_e32 v164, 64, v200
	v_add_u32_e32 v164, 64, v164
	v_cmp_lt_i32_e32 vcc, v162, v164
	v_max_f32_e32 v164, v34, v34
	s_nop 0
	v_cndmask_b32_e32 v162, v200, v162, vcc
	v_lshlrev_b32_e32 v222, 2, v162
	v_max_f32_e32 v162, v35, v35
	v_max_f32_e32 v162, v164, v162
	v_max3_f32 v162, v162, v36, v37
	v_max3_f32 v162, v162, v38, v39
	v_max3_f32 v162, v162, v40, v41
	v_max3_f32 v162, v162, v42, v43
	v_max3_f32 v162, v162, v44, v45
	v_max3_f32 v162, v162, v46, v47
	v_max3_f32 v162, v162, v48, v49
	v_max3_f32 v162, v162, v50, v51
	v_max3_f32 v162, v162, v52, v53
	v_max3_f32 v162, v162, v54, v55
	v_max3_f32 v162, v162, v56, v57
	v_max3_f32 v162, v162, v58, v59
	v_max3_f32 v162, v162, v60, v61
	v_max3_f32 v162, v162, v62, v63
	v_max3_f32 v162, v162, v64, v65
	v_mov_b32_e32 v164, v162
	s_nop 1
	v_permlane32_swap_b32_e32 v162, v164
	v_max_f32_e32 v164, v164, v164
	v_max_f32_e32 v162, v162, v164
	v_cmp_gt_f32_e32 vcc, v162, v163
	s_cbranch_vccz .LBB0_438
	v_max_f32_e32 v162, v162, v162
	v_max_f32_e32 v164, v163, v163
	v_max_f32_e32 v221, v164, v162
	v_sub_f32_e32 v162, v163, v221
	v_exp_f32_e32 v162, v162
	s_nop 0
	v_mul_f32_e32 v220, v220, v162
	v_pk_mul_f32 v[128:129], v[128:129], v[162:163] op_sel_hi:[1,0]
	v_pk_mul_f32 v[126:127], v[126:127], v[162:163] op_sel_hi:[1,0]
	v_pk_mul_f32 v[124:125], v[124:125], v[162:163] op_sel_hi:[1,0]
	v_pk_mul_f32 v[122:123], v[122:123], v[162:163] op_sel_hi:[1,0]
	v_pk_mul_f32 v[120:121], v[120:121], v[162:163] op_sel_hi:[1,0]
	v_pk_mul_f32 v[118:119], v[118:119], v[162:163] op_sel_hi:[1,0]
	v_pk_mul_f32 v[116:117], v[116:117], v[162:163] op_sel_hi:[1,0]
	v_pk_mul_f32 v[114:115], v[114:115], v[162:163] op_sel_hi:[1,0]
	v_pk_mul_f32 v[112:113], v[112:113], v[162:163] op_sel_hi:[1,0]
	v_pk_mul_f32 v[110:111], v[110:111], v[162:163] op_sel_hi:[1,0]
	v_pk_mul_f32 v[108:109], v[108:109], v[162:163] op_sel_hi:[1,0]
	v_pk_mul_f32 v[106:107], v[106:107], v[162:163] op_sel_hi:[1,0]
	v_pk_mul_f32 v[104:105], v[104:105], v[162:163] op_sel_hi:[1,0]
	v_pk_mul_f32 v[102:103], v[102:103], v[162:163] op_sel_hi:[1,0]
	v_pk_mul_f32 v[100:101], v[100:101], v[162:163] op_sel_hi:[1,0]
	v_pk_mul_f32 v[98:99], v[98:99], v[162:163] op_sel_hi:[1,0]
	s_branch .LBB0_439

.LBB0_439:
	v_sub_f32_e32 v34, v34, v221
	v_exp_f32_e32 v223, v34
	v_sub_f32_e32 v34, v35, v221
	v_exp_f32_e32 v224, v34
	v_sub_f32_e32 v34, v36, v221
	v_exp_f32_e32 v225, v34
	v_sub_f32_e32 v34, v37, v221
	v_exp_f32_e32 v226, v34
	v_sub_f32_e32 v34, v38, v221
	v_exp_f32_e32 v227, v34
	v_sub_f32_e32 v34, v39, v221
	v_exp_f32_e32 v228, v34
	v_sub_f32_e32 v34, v40, v221
	v_exp_f32_e32 v229, v34
	v_sub_f32_e32 v34, v41, v221
	v_exp_f32_e32 v230, v34
	v_sub_f32_e32 v34, v42, v221
	v_exp_f32_e32 v231, v34
	v_sub_f32_e32 v34, v43, v221
	v_exp_f32_e32 v232, v34
	v_sub_f32_e32 v34, v44, v221
	v_exp_f32_e32 v233, v34
	v_sub_f32_e32 v34, v45, v221
	v_exp_f32_e32 v234, v34
	v_sub_f32_e32 v34, v46, v221
	v_exp_f32_e32 v235, v34
	v_sub_f32_e32 v34, v47, v221
	v_exp_f32_e32 v236, v34
	v_sub_f32_e32 v34, v48, v221
	v_exp_f32_e32 v237, v34
	v_sub_f32_e32 v34, v49, v221
	v_exp_f32_e32 v238, v34
	v_sub_f32_e32 v34, v50, v221
	v_exp_f32_e32 v239, v34
	v_sub_f32_e32 v34, v51, v221
	v_exp_f32_e32 v240, v34
	v_sub_f32_e32 v34, v52, v221
	v_exp_f32_e32 v241, v34
	v_sub_f32_e32 v34, v53, v221
	v_exp_f32_e32 v242, v34
	v_sub_f32_e32 v34, v54, v221
	v_exp_f32_e32 v243, v34
	v_sub_f32_e32 v34, v55, v221
	v_exp_f32_e32 v244, v34
	v_sub_f32_e32 v34, v56, v221
	v_lshl_add_u32 v170, s3, 1, v217
	v_exp_f32_e32 v245, v34
	v_sub_f32_e32 v34, v57, v221
	v_exp_f32_e32 v246, v34
	v_sub_f32_e32 v34, v58, v221
	v_add_u32_e32 v38, 0x3000, v170
	v_add_u32_e32 v39, 0x4000, v170
	v_exp_f32_e32 v247, v34
	v_sub_f32_e32 v34, v59, v221
	ds_read2_b64 v[166:169], v38 offset0:128 offset1:130
	ds_read2_b64 v[162:165], v38 offset0:132 offset1:134
	ds_read2_b64 v[170:173], v39 offset0:192 offset1:194
	v_exp_f32_e32 v248, v34
	v_sub_f32_e32 v34, v60, v221
	v_exp_f32_e32 v249, v34
	v_sub_f32_e32 v34, v61, v221
	v_exp_f32_e32 v250, v34
	v_sub_f32_e32 v34, v62, v221
	v_exp_f32_e32 v251, v34
	v_sub_f32_e32 v34, v63, v221
	v_exp_f32_e32 v209, v34
	v_sub_f32_e32 v34, v64, v221
	v_exp_f32_e32 v212, v34
	v_sub_f32_e32 v34, v65, v221
	v_exp_f32_e32 v208, v34
	v_cvt_pk_bf16_f32 v34, v223, v224
	v_cvt_pk_bf16_f32 v35, v225, v226
	v_cvt_pk_bf16_f32 v36, v227, v228
	v_cvt_pk_bf16_f32 v37, v229, v230
	ds_read2_b64 v[174:177], v39 offset0:196 offset1:198
	ds_read2_b64 v[178:181], v38 offset0:136 offset1:138
	s_waitcnt lgkmcnt(4)
	v_mfma_f32_32x32x16_bf16 v[114:129], v[166:169], v[34:37], v[114:129]
	ds_read2_b64 v[182:185], v39 offset0:200 offset1:202
	ds_read2_b64 v[186:189], v38 offset0:140 offset1:142
	v_cvt_pk_bf16_f32 v202, v247, v248
	v_cvt_pk_bf16_f32 v203, v249, v250
	v_cvt_pk_bf16_f32 v204, v251, v209
	v_cvt_pk_bf16_f32 v205, v212, v208
	s_waitcnt lgkmcnt(4)
	v_mfma_f32_32x32x16_bf16 v[98:113], v[170:173], v[34:37], v[98:113]
	v_cvt_pk_bf16_f32 v34, v231, v232
	v_cvt_pk_bf16_f32 v35, v233, v234
	v_cvt_pk_bf16_f32 v36, v235, v236
	v_cvt_pk_bf16_f32 v37, v237, v238
	s_nop 1
	v_mfma_f32_32x32x16_bf16 v[114:129], v[162:165], v[34:37], v[114:129]
	s_waitcnt lgkmcnt(3)
	v_mfma_f32_32x32x16_bf16 v[98:113], v[174:177], v[34:37], v[98:113]
	v_cvt_pk_bf16_f32 v34, v239, v240
	v_cvt_pk_bf16_f32 v35, v241, v242
	v_cvt_pk_bf16_f32 v36, v243, v244
	v_cvt_pk_bf16_f32 v37, v245, v246
	s_waitcnt lgkmcnt(2)
	s_nop 0
	v_mfma_f32_32x32x16_bf16 v[114:129], v[178:181], v[34:37], v[114:129]
	s_waitcnt lgkmcnt(1)
	v_mfma_f32_32x32x16_bf16 v[98:113], v[182:185], v[34:37], v[98:113]
	ds_read2_b64 v[44:47], v39 offset0:204 offset1:206
	v_max_f32_e32 v34, v19, v19
	v_max_f32_e32 v35, v18, v18
	v_max_f32_e32 v34, v35, v34
	v_max3_f32 v34, v34, v20, v21
	v_max3_f32 v34, v34, v22, v23
	v_max3_f32 v34, v34, v24, v25
	v_max3_f32 v34, v34, v26, v27
	v_max3_f32 v34, v34, v28, v29
	v_max3_f32 v34, v34, v30, v31
	v_max3_f32 v34, v34, v32, v33
	v_max3_f32 v34, v34, v2, v3
	v_max3_f32 v34, v34, v4, v5
	v_max3_f32 v34, v34, v6, v7
	v_max3_f32 v34, v34, v8, v9
	v_max3_f32 v34, v34, v10, v11
	v_max3_f32 v34, v34, v12, v13
	v_max3_f32 v34, v34, v14, v15
	v_max3_f32 v34, v34, v16, v17
	s_waitcnt lgkmcnt(1)
	v_mfma_f32_32x32x16_bf16 v[114:129], v[186:189], v[202:205], v[114:129]
	v_mov_b32_e32 v35, v34
	s_nop 1
	v_permlane32_swap_b32_e32 v34, v35
	s_waitcnt lgkmcnt(0)
	v_max_f32_e32 v35, v35, v35
	v_max_f32_e32 v34, v34, v35
	v_mfma_f32_32x32x16_bf16 v[98:113], v[44:47], v[202:205], v[98:113]
	v_cmp_gt_f32_e32 vcc, v34, v0
	s_cbranch_vccz .LBB0_441
	v_max_f32_e32 v34, v34, v34
	v_max_f32_e32 v35, v0, v0
	v_max_f32_e32 v34, v35, v34
	v_sub_f32_e32 v0, v0, v34
	v_exp_f32_e32 v0, v0
	s_nop 0
	v_mul_f32_e32 v219, v219, v0
	v_pk_mul_f32 v[96:97], v[96:97], v[0:1] op_sel_hi:[1,0]
	v_pk_mul_f32 v[94:95], v[94:95], v[0:1] op_sel_hi:[1,0]
	v_pk_mul_f32 v[92:93], v[92:93], v[0:1] op_sel_hi:[1,0]
	v_pk_mul_f32 v[90:91], v[90:91], v[0:1] op_sel_hi:[1,0]
	v_pk_mul_f32 v[88:89], v[88:89], v[0:1] op_sel_hi:[1,0]
	v_pk_mul_f32 v[86:87], v[86:87], v[0:1] op_sel_hi:[1,0]
	v_pk_mul_f32 v[84:85], v[84:85], v[0:1] op_sel_hi:[1,0]
	v_pk_mul_f32 v[82:83], v[82:83], v[0:1] op_sel_hi:[1,0]
	v_pk_mul_f32 v[80:81], v[80:81], v[0:1] op_sel_hi:[1,0]
	v_pk_mul_f32 v[78:79], v[78:79], v[0:1] op_sel_hi:[1,0]
	v_pk_mul_f32 v[76:77], v[76:77], v[0:1] op_sel_hi:[1,0]
	v_pk_mul_f32 v[74:75], v[74:75], v[0:1] op_sel_hi:[1,0]
	v_pk_mul_f32 v[72:73], v[72:73], v[0:1] op_sel_hi:[1,0]
	v_pk_mul_f32 v[70:71], v[70:71], v[0:1] op_sel_hi:[1,0]
	v_pk_mul_f32 v[68:69], v[68:69], v[0:1] op_sel_hi:[1,0]
	v_pk_mul_f32 v[66:67], v[66:67], v[0:1] op_sel_hi:[1,0]
	v_mov_b32_e32 v0, v34

.LBB0_746:
	s_bitcmp1_b32 s11, 0
	s_cselect_b32 s12, 0x2c00, 0
	s_lshl_b32 s13, s12, 1
	v_add3_u32 v15, v192, s13, v191
	ds_read_b128 v[2:5], v15
	ds_read_b128 v[10:13], v194 offset:47104
	ds_read_b128 v[240:243], v15 offset:32
	ds_read_b128 v[216:219], v194 offset:47136
	ds_read_b128 v[244:247], v15 offset:64
	ds_read_b128 v[6:9], v194 offset:47168
	ds_read_b128 v[248:251], v15 offset:96
	ds_read_b128 v[220:223], v194 offset:47200
	s_waitcnt lgkmcnt(7)
	v_mfma_f32_32x32x16_bf16 v[112:127], v[2:5], v[144:147], 0
	s_waitcnt lgkmcnt(6)
	v_mfma_f32_32x32x16_bf16 v[96:111], v[2:5], v[10:13], 0
	ds_read_b128 v[2:5], v15 offset:128
	ds_read_b128 v[224:227], v194 offset:47232
	s_waitcnt lgkmcnt(7)
	v_mfma_f32_32x32x16_bf16 v[112:127], v[240:243], v[148:151], v[112:127]
	s_waitcnt lgkmcnt(6)
	v_mfma_f32_32x32x16_bf16 v[96:111], v[240:243], v[216:219], v[96:111]
	ds_read_b128 v[240:243], v15 offset:160
	ds_read_b128 v[228:231], v194 offset:47264
	s_waitcnt lgkmcnt(7)
	v_mfma_f32_32x32x16_bf16 v[112:127], v[244:247], v[152:155], v[112:127]
	s_waitcnt lgkmcnt(6)
	v_mfma_f32_32x32x16_bf16 v[96:111], v[244:247], v[6:9], v[96:111]
	ds_read_b128 v[244:247], v15 offset:6656
	s_waitcnt lgkmcnt(6)
	v_mfma_f32_32x32x16_bf16 v[112:127], v[248:251], v[156:159], v[112:127]
	s_waitcnt lgkmcnt(5)
	v_mfma_f32_32x32x16_bf16 v[96:111], v[248:251], v[220:223], v[96:111]
	ds_read_b128 v[248:251], v15 offset:6688
	s_waitcnt lgkmcnt(5)
	v_mfma_f32_32x32x16_bf16 v[112:127], v[2:5], v[160:163], v[112:127]
	s_waitcnt lgkmcnt(4)
	v_mfma_f32_32x32x16_bf16 v[96:111], v[2:5], v[224:227], v[96:111]
	ds_read_b128 v[2:5], v15 offset:6720
	s_waitcnt lgkmcnt(4)
	v_mfma_f32_32x32x16_bf16 v[112:127], v[240:243], v[164:167], v[112:127]
	s_waitcnt lgkmcnt(3)
	v_mfma_f32_32x32x16_bf16 v[96:111], v[240:243], v[228:231], v[96:111]
	ds_read_b128 v[240:243], v15 offset:6752
	s_waitcnt lgkmcnt(3)
	v_mfma_f32_32x32x16_bf16 v[128:143], v[244:247], v[144:147], 0
	v_mfma_f32_32x32x16_bf16 v[80:95], v[244:247], v[10:13], 0
	ds_read_b128 v[244:247], v15 offset:6784
	s_waitcnt lgkmcnt(3)
	v_mfma_f32_32x32x16_bf16 v[128:143], v[248:251], v[148:151], v[128:143]
	v_mfma_f32_32x32x16_bf16 v[80:95], v[248:251], v[216:219], v[80:95]
	ds_read_b128 v[248:251], v15 offset:6816
	s_waitcnt lgkmcnt(3)
	v_mfma_f32_32x32x16_bf16 v[128:143], v[2:5], v[152:155], v[128:143]
	v_mfma_f32_32x32x16_bf16 v[80:95], v[2:5], v[6:9], v[80:95]
	s_waitcnt lgkmcnt(2)
	v_mfma_f32_32x32x16_bf16 v[128:143], v[240:243], v[156:159], v[128:143]
	v_mfma_f32_32x32x16_bf16 v[80:95], v[240:243], v[220:223], v[80:95]
	s_waitcnt lgkmcnt(1)
	v_mfma_f32_32x32x16_bf16 v[128:143], v[244:247], v[160:163], v[128:143]
	v_mfma_f32_32x32x16_bf16 v[80:95], v[244:247], v[224:227], v[80:95]
	s_waitcnt lgkmcnt(0)
	v_mfma_f32_32x32x16_bf16 v[128:143], v[248:251], v[164:167], v[128:143]
	v_mfma_f32_32x32x16_bf16 v[80:95], v[248:251], v[228:231], v[80:95]
	v_max_f32_e32 v2, v113, v113
	v_max_f32_e32 v3, v112, v112
	v_max_f32_e32 v2, v3, v2
	v_max3_f32 v2, v2, v114, v115
	v_max3_f32 v2, v2, v116, v117
	v_max3_f32 v2, v2, v118, v119
	v_max3_f32 v2, v2, v120, v121
	v_max3_f32 v2, v2, v122, v123
	v_max3_f32 v2, v2, v124, v125
	v_max3_f32 v2, v2, v126, v127
	s_nop 0
	v_max3_f32 v2, v2, v128, v129
	v_max3_f32 v2, v2, v130, v131
	v_max3_f32 v2, v2, v132, v133
	v_max3_f32 v2, v2, v134, v135
	v_max3_f32 v2, v2, v136, v137
	v_max3_f32 v2, v2, v138, v139
	v_max3_f32 v2, v2, v140, v141
	v_max3_f32 v2, v2, v142, v143
	v_mov_b32_e32 v3, v2
	s_nop 1
	v_permlane32_swap_b32_e32 v2, v3
	v_max_f32_e32 v3, v3, v3
	v_max_f32_e32 v2, v2, v3
	v_add_f32_e32 v3, 0xc1000000, v2
	v_cmp_gt_f32_e32 vcc, v3, v215
	s_cbranch_vccz .LBB0_748
	v_max_f32_e32 v2, v2, v2
	v_max_f32_e32 v3, v215, v215
	v_max_f32_e32 v3, v3, v2
	v_sub_f32_e32 v2, v215, v3
	v_exp_f32_e32 v2, v2
	v_mov_b32_e32 v215, v3
	v_mul_f32_e32 v0, v0, v2
	v_pk_mul_f32 v[78:79], v[78:79], v[2:3] op_sel_hi:[1,0]
	v_pk_mul_f32 v[76:77], v[76:77], v[2:3] op_sel_hi:[1,0]
	v_pk_mul_f32 v[74:75], v[74:75], v[2:3] op_sel_hi:[1,0]
	v_pk_mul_f32 v[72:73], v[72:73], v[2:3] op_sel_hi:[1,0]
	v_pk_mul_f32 v[70:71], v[70:71], v[2:3] op_sel_hi:[1,0]
	v_pk_mul_f32 v[68:69], v[68:69], v[2:3] op_sel_hi:[1,0]
	v_pk_mul_f32 v[66:67], v[66:67], v[2:3] op_sel_hi:[1,0]
	v_pk_mul_f32 v[64:65], v[64:65], v[2:3] op_sel_hi:[1,0]
	v_pk_mul_f32 v[62:63], v[62:63], v[2:3] op_sel_hi:[1,0]
	v_pk_mul_f32 v[60:61], v[60:61], v[2:3] op_sel_hi:[1,0]
	v_pk_mul_f32 v[58:59], v[58:59], v[2:3] op_sel_hi:[1,0]
	v_pk_mul_f32 v[56:57], v[56:57], v[2:3] op_sel_hi:[1,0]
	v_pk_mul_f32 v[54:55], v[54:55], v[2:3] op_sel_hi:[1,0]
	v_pk_mul_f32 v[52:53], v[52:53], v[2:3] op_sel_hi:[1,0]
	v_pk_mul_f32 v[50:51], v[50:51], v[2:3] op_sel_hi:[1,0]
	v_pk_mul_f32 v[48:49], v[48:49], v[2:3] op_sel_hi:[1,0]
.LBB0_748:
	v_sub_f32_e32 v2, v112, v215
	v_sub_f32_e32 v3, v113, v215
	v_sub_f32_e32 v4, v114, v215
	v_sub_f32_e32 v5, v115, v215
	v_sub_f32_e32 v6, v116, v215
	v_sub_f32_e32 v7, v117, v215
	v_sub_f32_e32 v8, v118, v215
	v_sub_f32_e32 v9, v119, v215
	v_exp_f32_e32 v15, v2
	v_exp_f32_e32 v216, v3
	v_exp_f32_e32 v217, v4
	v_exp_f32_e32 v218, v5
	v_exp_f32_e32 v219, v6
	v_exp_f32_e32 v220, v7
	v_exp_f32_e32 v221, v8
	v_exp_f32_e32 v222, v9
	v_sub_f32_e32 v2, v120, v215
	v_sub_f32_e32 v3, v121, v215
	v_sub_f32_e32 v4, v122, v215
	v_sub_f32_e32 v5, v123, v215
	v_sub_f32_e32 v6, v124, v215
	v_sub_f32_e32 v7, v125, v215
	v_sub_f32_e32 v8, v126, v215
	v_sub_f32_e32 v9, v127, v215
	v_exp_f32_e32 v223, v2
	v_exp_f32_e32 v224, v3
	v_exp_f32_e32 v225, v4
	v_exp_f32_e32 v226, v5
	v_exp_f32_e32 v227, v6
	v_exp_f32_e32 v228, v7
	v_exp_f32_e32 v229, v8
	v_exp_f32_e32 v230, v9
	v_sub_f32_e32 v2, v128, v215
	v_sub_f32_e32 v3, v129, v215
	v_sub_f32_e32 v4, v130, v215
	v_sub_f32_e32 v5, v131, v215
	v_sub_f32_e32 v6, v132, v215
	v_sub_f32_e32 v7, v133, v215
	v_sub_f32_e32 v8, v134, v215
	v_sub_f32_e32 v9, v135, v215
	v_exp_f32_e32 v231, v2
	v_exp_f32_e32 v232, v3
	v_exp_f32_e32 v233, v4
	v_exp_f32_e32 v234, v5
	v_exp_f32_e32 v132, v6
	v_exp_f32_e32 v133, v7
	v_exp_f32_e32 v134, v8
	v_exp_f32_e32 v135, v9
	v_sub_f32_e32 v2, v136, v215
	v_sub_f32_e32 v3, v137, v215
	v_sub_f32_e32 v4, v138, v215
	v_sub_f32_e32 v5, v139, v215
	v_sub_f32_e32 v6, v140, v215
	v_sub_f32_e32 v7, v141, v215
	v_sub_f32_e32 v8, v142, v215
	v_sub_f32_e32 v9, v143, v215
	v_exp_f32_e32 v136, v2
	v_exp_f32_e32 v137, v3
	v_exp_f32_e32 v138, v4
	v_exp_f32_e32 v139, v5
	v_exp_f32_e32 v140, v6
	v_exp_f32_e32 v141, v7
	v_exp_f32_e32 v142, v8
	v_exp_f32_e32 v143, v9
	v_lshl_add_u32 v10, s12, 1, v214
	v_add_u32_e32 v128, 0x3000, v10
	v_add_u32_e32 v129, 0x4000, v10
	ds_read2_b64 v[6:9], v128 offset0:128 offset1:130
	ds_read2_b64 v[2:5], v128 offset0:132 offset1:134
	ds_read2_b64 v[10:13], v129 offset0:192 offset1:194
	v_cvt_pk_bf16_f32 v112, v15, v216
	v_cvt_pk_bf16_f32 v113, v217, v218
	v_cvt_pk_bf16_f32 v114, v219, v220
	v_cvt_pk_bf16_f32 v115, v221, v222
	v_cvt_pk_bf16_f32 v116, v223, v224
	v_cvt_pk_bf16_f32 v117, v225, v226
	s_waitcnt lgkmcnt(2)
	v_mfma_f32_32x32x16_bf16 v[64:79], v[6:9], v[112:115], v[64:79]
	v_cvt_pk_bf16_f32 v118, v227, v228
	v_cvt_pk_bf16_f32 v119, v229, v230
	ds_read2_b64 v[120:123], v129 offset0:200 offset1:202
	v_max_f32_e32 v202, v97, v97
	v_max_f32_e32 v203, v96, v96
	v_max_f32_e32 v202, v203, v202
	v_max3_f32 v202, v202, v98, v99
	s_waitcnt lgkmcnt(1)
	v_mfma_f32_32x32x16_bf16 v[48:63], v[10:13], v[112:115], v[48:63]
	ds_read2_b64 v[112:115], v129 offset0:196 offset1:198
	v_max3_f32 v202, v202, v100, v101
	v_max3_f32 v202, v202, v102, v103
	v_max3_f32 v202, v202, v104, v105
	v_max3_f32 v202, v202, v106, v107
	v_cvt_pk_bf16_f32 v124, v231, v232
	v_cvt_pk_bf16_f32 v125, v233, v234
	v_mfma_f32_32x32x16_bf16 v[64:79], v[2:5], v[116:119], v[64:79]
	v_cvt_pk_bf16_f32 v126, v132, v133
	v_cvt_pk_bf16_f32 v127, v134, v135
	v_max3_f32 v202, v202, v108, v109
	v_max3_f32 v202, v202, v110, v111
	v_max3_f32 v202, v202, v80, v81
	v_max3_f32 v202, v202, v82, v83
	v_max3_f32 v202, v202, v84, v85
	s_waitcnt lgkmcnt(0)
	v_mfma_f32_32x32x16_bf16 v[48:63], v[112:115], v[116:119], v[48:63]
	ds_read2_b64 v[116:119], v128 offset0:136 offset1:138
	v_max3_f32 v202, v202, v86, v87
	v_max3_f32 v202, v202, v88, v89
	v_max3_f32 v202, v202, v90, v91
	v_max3_f32 v202, v202, v92, v93
	v_cvt_pk_bf16_f32 v236, v136, v137
	v_cvt_pk_bf16_f32 v237, v138, v139
	s_waitcnt lgkmcnt(0)
	v_mfma_f32_32x32x16_bf16 v[64:79], v[116:119], v[124:127], v[64:79]
	v_cvt_pk_bf16_f32 v238, v140, v141
	v_cvt_pk_bf16_f32 v239, v142, v143
	v_max3_f32 v202, v202, v94, v95
	v_mov_b32_e32 v203, v202
	s_nop 1
	v_permlane32_swap_b32_e32 v202, v203
	v_max_f32_e32 v203, v203, v203
	v_mfma_f32_32x32x16_bf16 v[48:63], v[120:123], v[124:127], v[48:63]
	ds_read2_b64 v[124:127], v128 offset0:140 offset1:142
	ds_read2_b64 v[128:131], v129 offset0:204 offset1:206
	v_max_f32_e32 v208, v202, v203
	v_add_f32_e32 v203, 0xc1000000, v208
	v_cmp_gt_f32_e32 vcc, v203, v14
	s_waitcnt lgkmcnt(1)
	v_mfma_f32_32x32x16_bf16 v[64:79], v[124:127], v[236:239], v[64:79]
	s_waitcnt lgkmcnt(0)
	v_mfma_f32_32x32x16_bf16 v[48:63], v[128:131], v[236:239], v[48:63]
	s_cbranch_vccz .LBB0_750
	v_max_f32_e32 v202, v208, v208
	v_max_f32_e32 v203, v14, v14
	v_max_f32_e32 v202, v203, v202
	v_sub_f32_e32 v14, v14, v202
	v_exp_f32_e32 v14, v14
	s_nop 0
	v_mul_f32_e32 v195, v195, v14
	v_pk_mul_f32 v[46:47], v[46:47], v[14:15] op_sel_hi:[1,0]
	v_pk_mul_f32 v[44:45], v[44:45], v[14:15] op_sel_hi:[1,0]
	v_pk_mul_f32 v[42:43], v[42:43], v[14:15] op_sel_hi:[1,0]
	v_pk_mul_f32 v[40:41], v[40:41], v[14:15] op_sel_hi:[1,0]
	v_pk_mul_f32 v[38:39], v[38:39], v[14:15] op_sel_hi:[1,0]
	v_pk_mul_f32 v[36:37], v[36:37], v[14:15] op_sel_hi:[1,0]
	v_pk_mul_f32 v[34:35], v[34:35], v[14:15] op_sel_hi:[1,0]
	v_pk_mul_f32 v[32:33], v[32:33], v[14:15] op_sel_hi:[1,0]
	v_pk_mul_f32 v[30:31], v[30:31], v[14:15] op_sel_hi:[1,0]
	v_pk_mul_f32 v[28:29], v[28:29], v[14:15] op_sel_hi:[1,0]
	v_pk_mul_f32 v[26:27], v[26:27], v[14:15] op_sel_hi:[1,0]
	v_pk_mul_f32 v[24:25], v[24:25], v[14:15] op_sel_hi:[1,0]
	v_pk_mul_f32 v[22:23], v[22:23], v[14:15] op_sel_hi:[1,0]
	v_pk_mul_f32 v[20:21], v[20:21], v[14:15] op_sel_hi:[1,0]
	v_pk_mul_f32 v[18:19], v[18:19], v[14:15] op_sel_hi:[1,0]
	v_pk_mul_f32 v[16:17], v[16:17], v[14:15] op_sel_hi:[1,0]
	v_mov_b32_e32 v14, v202
